# attention: cost-weighted VALU spacing - softmax exps spread evenly over the MFMA shadows of QK(j+1) and both PV segments
# speedup vs baseline: 1.0072x; 1.0072x over previous
; #define LAS __attribute__((address_space(3)))
; template <bool FIRST>
; __device__ __forceinline__ void partialSM(f32x16& p0, f32x16& p1, f32x16& negm, float& dl, float& alpha) {
;     float pmax = p0[0];
; #pragma unroll
;     for (int r = 1; r < 16; ++r) pmax = fmaxf(pmax, p0[r]);
; #pragma unroll
;     for (int r = 0; r < 16; ++r) pmax = fmaxf(pmax, p1[r]);
;     { auto rr = __builtin_amdgcn_permlane32_swap(__float_as_uint(pmax), __float_as_uint(pmax), false, false);
;       pmax = fmaxf(__uint_as_float(rr[0]), __uint_as_float(rr[1])); }
;     if (FIRST) {
;         dl = 0.f; alpha = 1.f; const float d0_ = pmax - SH;
; #pragma unroll
;         for (int r = 0; r < 16; ++r) { p0[r] -= d0_; p1[r] -= d0_; negm[r] -= d0_; }
;     } else {
;         const bool keep = __all(pmax <= SH + THRL);
;         dl = keep ? 0.f : fmaxf(pmax - SH, 0.f); alpha = __builtin_amdgcn_exp2f(-dl);
;     }
; #pragma unroll
;     for (int r = 0; r < 16; ++r) p0[r] = __builtin_amdgcn_exp2f(p0[r]);
; }
; __device__ __forceinline__ void finishSM(f32x16& p0, f32x16& p1, v8i& pa) {
; #pragma unroll
;     for (int r = 0; r < 16; ++r) p1[r] = __builtin_amdgcn_exp2f(p1[r]);
; #pragma unroll
;     for (int w = 0; w < 4; ++w) { pa[w] = (int)pk4_fp8(p0[4 * w], p0[4 * w + 1], p0[4 * w + 2], p0[4 * w + 3]); pa[4 + w] = (int)pk4_fp8(p1[4 * w], p1[4 * w + 1], p1[4 * w + 2], p1[4 * w + 3]); }
; }
; __device__ __forceinline__ v8i ld32(const LAS char* a0, const LAS char* a1) { const v4i x = *(const LAS v4i*)a0, y = *(const LAS v4i*)a1; return (v8i){x[0], x[1], x[2], x[3], y[0], y[1], y[2], y[3]}; }
; __device__ __forceinline__ void qkt(f32x16& p0, f32x16& p1, const LAS char* Ks, int ka0, int ka1, const v8i* qf, const f32x16& negm) {
; #pragma unroll
;     for (int st = 0; st < 3; ++st) {
;         const v8i k0 = ld32(Ks + ka0 + 64 * st, Ks + ka1 + 64 * st), k1 = ld32(Ks + ka0 + 64 * st + 32 * 192, Ks + ka1 + 64 * st + 32 * 192);
;         if (st == 0) { p0 = MFMA8QK(k0, qf[st], negm); p1 = MFMA8QK(k1, qf[st], negm); }
;         else { p0 = MFMA8QK(k0, qf[st], p0); p1 = MFMA8QK(k1, qf[st], p1); } }
; }
; __device__ __forceinline__ void pv_d0(f32x16* o, const LAS char* Vs, int va0, int va1, v8i pa) {
; #pragma unroll
;     for (int d0 = 0; d0 < 4; ++d0) { const v8i vf = ld32(Vs + va0 + 2048 * d0, Vs + va1 + 2048 * d0); o[d0] = MFMA8(pa, vf, o[d0]); }
.LBB0_589:
	s_bitcmp1_b32 s15, 0
	s_cselect_b32 s0, 0x6000, 0
	s_add_i32 s0, s0, 0
	v_add_u32_e32 v0, s0, v244
	v_add_u32_e32 v210, s0, v245
	v_add_u32_e32 v211, 0xf000, v0
	v_add_u32_e32 v212, 0xf000, v210
	ds_read_b128 v[2:5], v0 offset:61504
	ds_read_b128 v[6:9], v210 offset:61504
	v_exp_f32_e32 v14, v116
	v_exp_f32_e32 v15, v117
	v_exp_f32_e32 v12, v114
	v_exp_f32_e32 v13, v115
	s_waitcnt lgkmcnt(4)
	v_mfma_scale_f32_32x32x64_f8f6f4 v[144:159], v[202:209], v[184:191], v[96:111], v234, v233 op_sel_hi:[0,0,0]
	ds_read_b128 v[202:205], v211 offset:6208
	ds_read_b128 v[206:209], v212 offset:6208
	v_exp_f32_e32 v114, v118
	v_exp_f32_e32 v115, v119
	v_exp_f32_e32 v119, v120
	v_exp_f32_e32 v120, v121
	v_cvt_pk_fp8_f32 v117, v14, v15
	v_exp_f32_e32 v10, v112
	v_exp_f32_e32 v11, v113
	s_waitcnt lgkmcnt(4)
	v_mfma_scale_f32_32x32x64_f8f6f4 v[128:143], v[194:201], v[184:191], v[96:111], v234, v233 op_sel_hi:[0,0,0]
	ds_read_b128 v[194:197], v0 offset:61568
	ds_read_b128 v[198:201], v210 offset:61568
	v_exp_f32_e32 v121, v122
	v_exp_f32_e32 v122, v123
	v_exp_f32_e32 v123, v124
	v_exp_f32_e32 v124, v125
	v_cvt_pk_fp8_f32 v117, v114, v115 op_sel:[0,0,1]
	v_cvt_pk_fp8_f32 v118, v119, v120
	v_exp_f32_e32 v125, v126
	s_waitcnt lgkmcnt(4)
	v_mfma_scale_f32_32x32x64_f8f6f4 v[144:159], v[2:9], v[176:183], v[144:159], v234, v233 op_sel_hi:[0,0,0]
	ds_read_b128 v[2:5], v211 offset:6272
	ds_read_b128 v[6:9], v212 offset:6272
	v_exp_f32_e32 v126, v127
	v_cvt_pk_fp8_f32 v112, v228, v229
	v_cvt_pk_fp8_f32 v116, v10, v11
	v_cvt_pk_fp8_f32 v113, v226, v227
	v_cvt_pk_fp8_f32 v114, v222, v223
	v_cvt_pk_fp8_f32 v115, v166, v167
	s_waitcnt lgkmcnt(4)
	v_mfma_scale_f32_32x32x64_f8f6f4 v[128:143], v[202:209], v[176:183], v[128:143], v234, v233 op_sel_hi:[0,0,0]
	v_cvt_pk_fp8_f32 v119, v123, v124
	v_cvt_pk_fp8_f32 v112, v220, v221 op_sel:[0,0,1]
	v_cvt_pk_fp8_f32 v116, v12, v13 op_sel:[0,0,1]
	v_cvt_pk_fp8_f32 v113, v224, v225 op_sel:[0,0,1]
	v_cvt_pk_fp8_f32 v114, v162, v163 op_sel:[0,0,1]
	v_cvt_pk_fp8_f32 v118, v121, v122 op_sel:[0,0,1]
	s_waitcnt lgkmcnt(2)
	v_mfma_scale_f32_32x32x64_f8f6f4 v[144:159], v[194:201], v[168:175], v[144:159], v234, v233 op_sel_hi:[0,0,0]
	v_cvt_pk_fp8_f32 v115, v164, v165 op_sel:[0,0,1]
	v_cvt_pk_fp8_f32 v119, v125, v126 op_sel:[0,0,1]
	v_mov_b32_e32 v161, v160
	v_mov_b32_e32 v162, v160
	v_mov_b32_e32 v163, v160
	s_waitcnt lgkmcnt(0)
	v_mfma_scale_f32_32x32x64_f8f6f4 v[128:143], v[2:9], v[168:175], v[128:143], v234, v233 op_sel_hi:[0,0,0]
	v_mov_b32_e32 v164, v160
	v_mov_b32_e32 v165, v160
	v_mov_b32_e32 v166, v160
	v_mov_b32_e32 v167, v160
	s_add_i32 s66, s21, -2
	s_ashr_i32 s38, s66, 1
	s_mul_hi_i32 s0, s38, 0x55555556
	s_lshr_b32 s1, s0, 31
	s_add_i32 s0, s0, s1
	s_mul_i32 s0, s0, 3
	s_sub_i32 s0, s38, s0
	s_lshl_b32 s0, s0, 14
	s_add_i32 s0, s0, 0
	v_add_u32_e32 v0, s0, v241
	v_add_u32_e32 v11, s0, v240
	ds_read_b128 v[208:211], v0
	ds_read_b128 v[212:215], v11
	ds_read_b128 v[200:203], v0 offset:2048
	ds_read_b128 v[204:207], v11 offset:2048
	ds_read_b128 v[192:195], v0 offset:4096
	ds_read_b128 v[196:199], v11 offset:4096
	ds_read_b128 v[2:5], v0 offset:6144
	ds_read_b128 v[6:9], v11 offset:6144
	v_mov_b32_e32 v125, 0x19000
	v_lshl_add_u32 v126, v216, 4, v125
	v_lshl_add_u32 v127, v216, 2, v125
	ds_read_b128 v[120:123], v126
	ds_read_b32 v124, v127 offset:8192
	v_max_f32_e32 v0, v144, v145
	v_max3_f32 v0, v0, v146, v147
	v_max3_f32 v0, v0, v148, v149
	v_max3_f32 v0, v0, v150, v151
	v_max3_f32 v0, v0, v152, v153
	v_max3_f32 v0, v0, v154, v155
	v_max3_f32 v0, v0, v156, v157
	v_max3_f32 v0, v0, v158, v159
	s_waitcnt lgkmcnt(8)
	v_mfma_scale_f32_32x32x64_f8f6f4 v[64:79], v[112:119], v[208:215], v[64:79], v234, v234 op_sel_hi:[0,0,0]
	v_exp_f32_e32 v14, v144
	v_exp_f32_e32 v15, v145
	v_exp_f32_e32 v10, v148
	v_exp_f32_e32 v11, v149
	v_max3_f32 v0, v0, v128, v129
	v_max3_f32 v0, v0, v130, v131
	v_max3_f32 v0, v0, v132, v133
	v_max3_f32 v0, v0, v134, v135
	s_waitcnt lgkmcnt(6)
	v_mfma_scale_f32_32x32x64_f8f6f4 v[48:63], v[112:119], v[200:207], v[48:63], v234, v234 op_sel_hi:[0,0,0]
	v_exp_f32_e32 v12, v150
	v_exp_f32_e32 v13, v151
	v_max3_f32 v0, v0, v136, v137
	v_max3_f32 v0, v0, v138, v139
	v_max3_f32 v0, v0, v140, v141
	v_max3_f32 v0, v0, v142, v143
	s_waitcnt lgkmcnt(4)
	v_mfma_scale_f32_32x32x64_f8f6f4 v[32:47], v[112:119], v[192:199], v[32:47], v234, v234 op_sel_hi:[0,0,0]
	v_exp_f32_e32 v192, v146
	v_exp_f32_e32 v193, v147
	v_mov_b32_e32 v125, v0
	s_nop 1
	v_permlane32_swap_b32_e32 v0, v125
	s_waitcnt lgkmcnt(2)
	v_mfma_scale_f32_32x32x64_f8f6f4 v[16:31], v[112:119], v[2:9], v[16:31], v234, v234 op_sel_hi:[0,0,0]
	v_exp_f32_e32 v6, v152
	v_exp_f32_e32 v7, v153
	v_exp_f32_e32 v8, v154
	v_exp_f32_e32 v9, v155
	v_mfma_scale_f32_32x32x64_f8f6f4 v[80:95], v[112:119], v[160:167], v[80:95], v234, v234 op_sel_hi:[0,0,0]
	v_exp_f32_e32 v2, v156
	v_exp_f32_e32 v3, v157
	v_exp_f32_e32 v4, v158
	v_exp_f32_e32 v5, v159
	s_waitcnt vmcnt(0) lgkmcnt(0)
	s_barrier
	v_max_f32_e32 v0, v0, v125
	s_add_i32 s42, s38, 2
	v_cmp_ge_f32_e64 s[0:1], s67, v0
	s_cmp_ge_i32 s42, s14
	s_cbranch_scc1 .Lattn_noissue
	s_bitcmp1_b32 s21, 1
	s_cselect_b32 s44, 0x6000, 0
	v_add_u32_e32 v126, s44, v244
	v_add_u32_e32 v127, s44, v245
	ds_read_b128 v[208:211], v126 offset:49152
	ds_read_b128 v[212:215], v127 offset:49152
	s_ashr_i32 s43, s42, 31
	s_mul_i32 s38, s42, 0x18000
	s_mul_hi_i32 s39, s42, 0x18000
	s_add_u32 s38, s24, s38
	s_addc_u32 s39, s25, s39
	s_lshl_b64 s[40:41], s[42:43], 14
	s_add_u32 s40, s52, s40
	s_addc_u32 s41, s53, s41
	s_mul_hi_i32 s43, s42, 0x55555556
	s_lshr_b32 s67, s43, 31
	s_add_i32 s43, s43, s67
	s_mul_i32 s43, s43, 3
	s_sub_i32 s42, s42, s43
	s_lshl_b32 s67, s42, 14
	s_bitcmp1_b32 s66, 1
	s_mov_b32 s42, 0xa000
	s_cselect_b32 s66, 0x10000, s42
	s_and_b64 vcc, exec, s[6:7]
	s_cbranch_vccnz .Lattn_iss_hi
	s_add_i32 m0, s67, s28
	s_nop 0
	global_load_lds_dwordx4 v120, s[40:41]
	s_add_i32 m0, s2, s66
	s_nop 0
	global_load_lds_dwordx4 v121, s[38:39]
	s_add_i32 m0, s27, s66
	s_nop 0
	global_load_lds_dwordx4 v122, s[38:39]
	s_add_i32 m0, s67, s31
	s_nop 0
	global_load_lds_dwordx4 v123, s[40:41]
	s_add_i32 m0, s33, s66
	s_nop 0
	global_load_lds_dwordx4 v124, s[38:39]
	s_branch .Lattn_iss_done

; #define LAS __attribute__((address_space(3)))
; template <bool FIRST>
; __device__ __forceinline__ void partialSM(f32x16& p0, f32x16& p1, f32x16& negm, float& dl, float& alpha) {
;     float pmax = p0[0];
; #pragma unroll
;     for (int r = 1; r < 16; ++r) pmax = fmaxf(pmax, p0[r]);
; #pragma unroll
;     for (int r = 0; r < 16; ++r) pmax = fmaxf(pmax, p1[r]);
;     { auto rr = __builtin_amdgcn_permlane32_swap(__float_as_uint(pmax), __float_as_uint(pmax), false, false);
;       pmax = fmaxf(__uint_as_float(rr[0]), __uint_as_float(rr[1])); }
;     if (FIRST) {
;         dl = 0.f; alpha = 1.f; const float d0_ = pmax - SH;
; #pragma unroll
;         for (int r = 0; r < 16; ++r) { p0[r] -= d0_; p1[r] -= d0_; negm[r] -= d0_; }
;     } else {
;         const bool keep = __all(pmax <= SH + THRL);
;         dl = keep ? 0.f : fmaxf(pmax - SH, 0.f); alpha = __builtin_amdgcn_exp2f(-dl);
;     }
; #pragma unroll
;     for (int r = 0; r < 16; ++r) p0[r] = __builtin_amdgcn_exp2f(p0[r]);
; }
; __device__ __forceinline__ void finishSM(f32x16& p0, f32x16& p1, v8i& pa) {
; #pragma unroll
;     for (int r = 0; r < 16; ++r) p1[r] = __builtin_amdgcn_exp2f(p1[r]);
; #pragma unroll
;     for (int w = 0; w < 4; ++w) { pa[w] = (int)pk4_fp8(p0[4 * w], p0[4 * w + 1], p0[4 * w + 2], p0[4 * w + 3]); pa[4 + w] = (int)pk4_fp8(p1[4 * w], p1[4 * w + 1], p1[4 * w + 2], p1[4 * w + 3]); }
; }
; __device__ __forceinline__ v8i ld32(const LAS char* a0, const LAS char* a1) { const v4i x = *(const LAS v4i*)a0, y = *(const LAS v4i*)a1; return (v8i){x[0], x[1], x[2], x[3], y[0], y[1], y[2], y[3]}; }
; __device__ __forceinline__ void qkt(f32x16& p0, f32x16& p1, const LAS char* Ks, int ka0, int ka1, const v8i* qf, const f32x16& negm) {
; #pragma unroll
;     for (int st = 0; st < 3; ++st) {
;         const v8i k0 = ld32(Ks + ka0 + 64 * st, Ks + ka1 + 64 * st), k1 = ld32(Ks + ka0 + 64 * st + 32 * 192, Ks + ka1 + 64 * st + 32 * 192);
;         if (st == 0) { p0 = MFMA8QK(k0, qf[st], negm); p1 = MFMA8QK(k1, qf[st], negm); }
;         else { p0 = MFMA8QK(k0, qf[st], p0); p1 = MFMA8QK(k1, qf[st], p1); } }
; }
; __device__ __forceinline__ void pv_d0(f32x16* o, const LAS char* Vs, int va0, int va1, v8i pa) {
; #pragma unroll
;     for (int d0 = 0; d0 < 4; ++d0) { const v8i vf = ld32(Vs + va0 + 2048 * d0, Vs + va1 + 2048 * d0); o[d0] = MFMA8(pa, vf, o[d0]); }
.LBB0_615:
	s_mul_hi_u32 s0, s15, 0xaaaaaaab
	s_lshr_b32 s0, s0, 1
	s_mul_i32 s0, s0, 0xffff4000
	s_bfe_i32 s1, s21, 0x10001
	s_and_b32 s1, s1, 0x6000
	s_add_i32 s1, s1, 0
	v_add_u32_e32 v0, s1, v244
	v_add_u32_e32 v161, s1, v245
	ds_read_b128 v[194:197], v0 offset:55360
	ds_read_b128 v[198:201], v161 offset:55360
	v_exp_f32_e32 v129, v129
	v_exp_f32_e32 v162, v133
	s_waitcnt lgkmcnt(4)
	v_mfma_scale_f32_32x32x64_f8f6f4 v[144:159], v[208:215], v[184:191], v[96:111], v234, v233 op_sel_hi:[0,0,0]
	ds_read_b128 v[202:205], v0 offset:49216
	ds_read_b128 v[206:209], v161 offset:49216
	v_exp_f32_e32 v130, v130
	v_exp_f32_e32 v131, v131
	v_exp_f32_e32 v134, v134
	v_exp_f32_e32 v135, v135
	s_waitcnt lgkmcnt(4)
	v_mfma_scale_f32_32x32x64_f8f6f4 v[112:127], v[120:127], v[184:191], v[96:111], v234, v233 op_sel_hi:[0,0,0]
	v_exp_f32_e32 v136, v136
	v_exp_f32_e32 v137, v137
	v_exp_f32_e32 v140, v140
	v_exp_f32_e32 v141, v141
	s_waitcnt lgkmcnt(2)
	v_mfma_scale_f32_32x32x64_f8f6f4 v[112:127], v[194:201], v[176:183], v[112:127], v234, v233 op_sel_hi:[0,0,0]
	v_exp_f32_e32 v138, v138
	v_exp_f32_e32 v139, v139
	v_exp_f32_e32 v142, v142
	v_exp_f32_e32 v143, v143
	s_waitcnt lgkmcnt(0)
	v_mfma_scale_f32_32x32x64_f8f6f4 v[144:159], v[202:209], v[176:183], v[144:159], v234, v233 op_sel_hi:[0,0,0]
	ds_read_b128 v[194:197], v0 offset:55424
	ds_read_b128 v[198:201], v161 offset:55424
	ds_read_b128 v[202:205], v0 offset:49280
	ds_read_b128 v[206:209], v161 offset:49280
	v_exp_f32_e32 v0, v128
	v_exp_f32_e32 v161, v132
	v_cvt_pk_fp8_f32 v132, v0, v129
	v_cvt_pk_fp8_f32 v133, v161, v162
	v_cvt_pk_fp8_f32 v128, v14, v15
	v_cvt_pk_fp8_f32 v132, v130, v131 op_sel:[0,0,1]
	v_cvt_pk_fp8_f32 v133, v134, v135 op_sel:[0,0,1]
	s_waitcnt lgkmcnt(0)
	v_mfma_scale_f32_32x32x64_f8f6f4 v[112:127], v[194:201], v[168:175], v[112:127], v234, v233 op_sel_hi:[0,0,0]
	v_cvt_pk_fp8_f32 v129, v10, v11
	v_cvt_pk_fp8_f32 v130, v6, v7
	v_cvt_pk_fp8_f32 v134, v136, v137
	v_cvt_pk_fp8_f32 v131, v2, v3
	v_cvt_pk_fp8_f32 v135, v140, v141
	v_cvt_pk_fp8_f32 v128, v192, v193 op_sel:[0,0,1]
	v_cvt_pk_fp8_f32 v129, v12, v13 op_sel:[0,0,1]
	v_cvt_pk_fp8_f32 v130, v8, v9 op_sel:[0,0,1]
	v_cvt_pk_fp8_f32 v134, v138, v139 op_sel:[0,0,1]
	v_cvt_pk_fp8_f32 v131, v4, v5 op_sel:[0,0,1]
	v_cvt_pk_fp8_f32 v135, v142, v143 op_sel:[0,0,1]
	v_or_b32_e32 v10, s0, v218
	v_or_b32_e32 v11, s0, v250
	v_add_u32_e32 v10, v247, v10
	v_add_u32_e32 v11, v247, v11
	ds_read_b128 v[2:5], v10
	ds_read_b128 v[6:9], v11
	v_mfma_scale_f32_32x32x64_f8f6f4 v[144:159], v[202:209], v[168:175], v[144:159], v234, v233 op_sel_hi:[0,0,0]
	ds_read_b128 v[194:197], v10 offset:2048
	ds_read_b128 v[198:201], v11 offset:2048
	v_mov_b32_e32 v161, v160
	v_mov_b32_e32 v162, v160
	v_mov_b32_e32 v163, v160
	v_mov_b32_e32 v164, v160
	v_mov_b32_e32 v165, v160
	v_mov_b32_e32 v166, v160
	v_mov_b32_e32 v167, v160
	s_waitcnt lgkmcnt(2)
	v_mfma_scale_f32_32x32x64_f8f6f4 v[64:79], v[128:135], v[2:9], v[64:79], v234, v234 op_sel_hi:[0,0,0]
	ds_read_b128 v[2:5], v10 offset:4096
	ds_read_b128 v[6:9], v11 offset:4096
	s_waitcnt lgkmcnt(2)
	v_mfma_scale_f32_32x32x64_f8f6f4 v[48:63], v[128:135], v[194:201], v[48:63], v234, v234 op_sel_hi:[0,0,0]
	ds_read_b128 v[194:197], v10 offset:6144
	ds_read_b128 v[198:201], v11 offset:6144
	s_nop 2
	v_exp_f32_e32 v228, v144
	v_exp_f32_e32 v229, v145
	v_exp_f32_e32 v220, v146
	v_exp_f32_e32 v221, v147
	v_exp_f32_e32 v226, v148
	s_waitcnt lgkmcnt(2)
	v_mfma_scale_f32_32x32x64_f8f6f4 v[32:47], v[128:135], v[2:9], v[32:47], v234, v234 op_sel_hi:[0,0,0]
	v_exp_f32_e32 v227, v149
	v_exp_f32_e32 v224, v150
	v_exp_f32_e32 v225, v151
	v_exp_f32_e32 v222, v152
	v_exp_f32_e32 v223, v153
	v_max_f32_e32 v0, v144, v145
	v_max3_f32 v0, v0, v146, v147
	v_max3_f32 v0, v0, v148, v149
	v_max3_f32 v0, v0, v150, v151
	v_max3_f32 v0, v0, v152, v153
	s_waitcnt lgkmcnt(0)
	v_mfma_scale_f32_32x32x64_f8f6f4 v[16:31], v[128:135], v[194:201], v[16:31], v234, v234 op_sel_hi:[0,0,0]
	s_bitcmp0_b32 s15, 0
	s_cselect_b32 s1, 0x6000, 0
	v_add_u32_e32 v12, s1, v244
	v_add_u32_e32 v13, s1, v245
	v_add_u32_e32 v14, 0xf000, v12
	v_add_u32_e32 v15, 0xf000, v13
	ds_read_b128 v[202:205], v12 offset:61440
	ds_read_b128 v[206:209], v13 offset:61440
	ds_read_b128 v[194:197], v14 offset:6144
	ds_read_b128 v[198:201], v15 offset:6144
	v_max3_f32 v0, v0, v154, v155
	v_max3_f32 v0, v0, v156, v157
	v_max3_f32 v0, v0, v158, v159
	v_max3_f32 v0, v0, v112, v113
	v_max3_f32 v0, v0, v114, v115
	v_max3_f32 v0, v0, v116, v117
	v_max3_f32 v0, v0, v118, v119
	v_max3_f32 v0, v0, v120, v121
	v_max3_f32 v0, v0, v122, v123
	v_mfma_scale_f32_32x32x64_f8f6f4 v[80:95], v[128:135], v[160:167], v[80:95], v234, v234 op_sel_hi:[0,0,0]
	v_max3_f32 v0, v0, v124, v125
	v_max3_f32 v0, v0, v126, v127
	v_mov_b32_e32 v2, v0
	s_nop 1
	v_permlane32_swap_b32_e32 v0, v2
	v_max_f32_e32 v0, v0, v2
	v_cmp_ge_f32_e32 vcc, s67, v0
	v_exp_f32_e32 v162, v154
	s_cmp_lg_u64 vcc, exec
	v_exp_f32_e32 v163, v155
	v_exp_f32_e32 v166, v156
	v_exp_f32_e32 v167, v157
	v_exp_f32_e32 v164, v158
	v_exp_f32_e32 v165, v159
	s_cbranch_scc0 .LBB0_588
	v_add_f32_e32 v2, -4.0, v0
	v_max_f32_e32 v2, 0, v2
	v_exp_f32_e64 v0, -v2
	s_and_saveexec_b64 s[0:1], s[12:13]
	s_cbranch_execz .LBB0_587
	ds_write_b32 v243, v0 offset:128
	s_branch .LBB0_587
